# split-phase grid barrier 3: arrive after phase 3, moba starts at once (KT scratch moved out of hbuf), scan runs after the first moba item behind the barrier wait, remaining moba items dealt from a per
# speedup vs baseline: 1.0066x; 1.0066x over previous
.LBB0_363:
	s_or_b64 exec, exec, s[4:5]
	s_cmpk_gt_i32 s76, 0x63f
	s_waitcnt lgkmcnt(0)
	s_barrier
	s_cbranch_scc1 .LBB0_429
	s_add_i32 s0, s42, 0xffffff00
	s_cmpk_gt_i32 s76, 0xff
	s_cselect_b32 s0, s0, 0x640
	s_cmpk_gt_i32 s42, 0x1ff
	s_cselect_b32 s39, s0, s42
	s_add_u32 s6, s58, 0xa00000
	v_writelane_b32 v255, s94, 5
	s_addc_u32 s7, s59, 0
	s_add_u32 s0, s72, 0x400000
	v_writelane_b32 v255, s95, 6
	v_writelane_b32 v255, s0, 7
	s_addc_u32 s0, s73, 0
	v_writelane_b32 v255, s0, 8
	s_add_u32 s0, s58, 0x800000
	v_writelane_b32 v255, s0, 9
	s_addc_u32 s0, s59, 0
	s_add_u32 s80, s58, 0x600000
	s_addc_u32 s81, s59, 0
	s_add_u32 s70, s70, 0xc00000
	s_addc_u32 s71, s71, 0
	s_add_u32 s8, s58, 0x2cd1000
	s_addc_u32 s9, s59, 0
	s_add_u32 s10, s58, 0xccd1000
	s_addc_u32 s11, s59, 0
	s_add_u32 s82, s58, 0xbcd1000
	s_addc_u32 s83, s59, 0
	s_mov_b32 s84, s56
	s_mov_b32 s85, s57
	s_add_u32 s12, s58, 0xa40000
	s_addc_u32 s13, s59, 0
	s_add_u32 s28, s58, 0xc50000
	s_addc_u32 s29, s59, 0
	s_add_u32 s30, s58, 0xc90000
	s_addc_u32 s31, s59, 0
	s_add_u32 s86, s58, 0xcd0000
	s_addc_u32 s87, s59, 0
	s_add_u32 s88, s58, 0xdcd1000
	s_addc_u32 s89, s59, 0
	v_mbcnt_lo_u32_b32 v0, -1, 0
	s_add_u32 s34, s58, 0xa40060
	v_mbcnt_hi_u32_b32 v234, -1, v0
	v_bfrev_b32_e32 v0, 0.5
	v_writelane_b32 v255, s0, 10
	s_addc_u32 s35, s59, 0
	v_mov_b32_e32 v205, 0
	s_movk_i32 s90, 0x104
	s_movk_i32 s91, 0x3000
	s_movk_i32 s92, 0x1000
	s_movk_i32 s93, 0x1800
	s_movk_i32 s94, 0x2000
	s_movk_i32 s95, 0x4000
	s_mov_b32 s96, 0x9cd1000
	s_mov_b32 s97, 0xacd1000
	s_mov_b32 s33, 0xccd1000
	s_mov_b32 s74, 0xcd1000
	s_mov_b32 s75, 0xbcd1000
	s_movk_i32 s78, 0x200
	v_mov_b32_e32 v254, 0x7f800000
	v_mov_b32_e32 v232, 0x7fc00000
	v_mov_b32_e32 v233, 0xff800000
	v_lshl_or_b32 v235, v234, 2, v0
	s_mov_b32 s2, s76
	s_mov_b32 s77, s76
	s_mov_b32 s37, 0
	s_mov_b32 s38, 0x3db504f3
	s_mov_b64 s[40:41], 0x2000
	s_mov_b64 s[62:63], 0xc00
	s_branch .LBB0_367

.LBB0_429:
	s_waitcnt vmcnt(0)
	s_barrier
	s_mov_b64 s[4:5], exec
	v_readlane_b32 s0, v255, 1
	v_readlane_b32 s1, v255, 2
	s_and_b64 s[0:1], s[4:5], s[0:1]
	s_mov_b64 exec, s[0:1]
	s_cbranch_execz .LBB0_481
	v_readlane_b32 s94, v255, 5
	v_readlane_b32 s95, v255, 6
	v_mov_b32_e32 v0, 0x10000
	s_waitcnt vmcnt(0) expcnt(0) lgkmcnt(0)
	ds_read_b32 v2, v0
	v_mov_b32_e32 v0, 0x10004
	ds_read_b32 v5, v0
	s_lshl_b32 s0, s3, 8
	s_add_u32 s6, s94, s0
	s_addc_u32 s7, s95, 0
	v_mov_b32_e32 v3, 0x1000
	v_mov_b32_e32 v4, 1
	global_atomic_add v3, v3, v4, s[6:7] offset:1024 sc0
	s_waitcnt vmcnt(0) lgkmcnt(0)
	v_add_u32_e32 v3, 1, v3
	v_lshlrev_b32_e32 v6, 2, v2
	v_cmp_eq_u32_e32 vcc, v3, v6
	s_cbranch_vccz .Lb3_arr_done
	buffer_wbl2 sc1
	s_waitcnt vmcnt(0)
	v_mov_b32_e32 v3, 0x3000
	global_atomic_add v3, v3, v4, s[94:95] offset:1024 sc0
	v_readlane_b32 s0, v255, 11
	s_nop 3
	s_sub_i32 s0, 4, s0
	s_nop 0
	v_mul_lo_u32 v6, v5, s0
	s_waitcnt vmcnt(0)
	v_add_u32_e32 v3, 1, v3
	v_cmp_eq_u32_e32 vcc, v3, v6
	s_cbranch_vccz .Lb3_not_last
	v_mov_b32_e32 v3, 0x3500
	global_atomic_add v3, v4, s[94:95]
.Lb3_not_last:
	v_mov_b32_e32 v3, 0x2000
	global_atomic_add v3, v4, s[6:7] offset:1024
.Lb3_arr_done:
.LBB0_481:
	s_or_b64 exec, exec, s[4:5]
	s_mov_b32 s98, 0
	s_nop 0
	v_writelane_b32 v255, s98, 14
	s_branch .LBB0_486
.Lscan_entry:
	s_mov_b32 s2, 0xfe03f81
	s_mov_b32 s18, 0xcd0000
	s_mov_b64 s[16:17], 0x40800
	s_mov_b32 s19, s76

.LBB0_565:
	s_cbranch_execz .LBB0_643
	s_lshl_b32 s0, s76, 2
	s_and_b32 s73, s0, 28
	s_lshl_b32 s0, s76, 11
	s_ashr_i32 s33, s76, 3
	s_and_b32 s52, s0, 0x3000
	s_ashr_i32 s2, s42, 3
	s_not_b32 s72, s33
	s_or_b32 s74, s52, 64
	s_add_u32 s66, s58, 0x2cd1000
	s_addc_u32 s67, s59, 0
	s_add_u32 s75, s58, 0x8cd1000
	s_addc_u32 s77, s59, 0
	s_add_u32 s78, s58, 0xbd0000
	v_mbcnt_lo_u32_b32 v0, -1, 0
	s_addc_u32 s79, s59, 0
	v_mbcnt_hi_u32_b32 v196, -1, v0
	s_mov_b32 s63, 0
	s_add_u32 s68, s58, 0xcd1000
	v_and_b32_e32 v0, 64, v196
	s_mov_b32 s53, s63
	s_addc_u32 s69, s59, 0
	v_mov_b32_e32 v33, 0
	s_movk_i32 s80, 0xff
	s_movk_i32 s81, 0x1800
	s_mov_b32 s82, 0xefa18f08
	v_xor_b32_e32 v197, 32, v196
	v_add_u32_e32 v198, 64, v0
	v_mov_b32_e32 v199, 0xff800000
	v_mov_b32_e32 v200, 0x3f803f80
	s_mov_b32 s6, 0
	s_mov_b32 s83, 0
	v_readlane_b32 s98, v255, 14
	s_nop 3
	s_cmp_lg_u32 s98, 0
	s_cbranch_scc1 .Lmoba_dq_latch2
	s_branch .LBB0_569
.LBB0_567:
	v_readlane_b32 s100, v255, 1
	v_readlane_b32 s101, v255, 2
	s_mov_b64 s[98:99], exec
	s_nop 1
	s_mov_b64 exec, s[100:101]
	s_cbranch_execz .Lmoba_dq_pub_skip
	v_mov_b32_e32 v217, 0x10008
	ds_write_b32 v217, v254
.Lmoba_dq_pub_skip:
	s_mov_b64 exec, s[98:99]
	global_load_dwordx4 v[0:3], v[180:181], off offset:3072
	global_load_dwordx4 v[4:7], v[180:181], off offset:3104
	v_and_or_b32 v8, v196, 64, v201
	v_lshlrev_b32_e32 v8, 2, v8
	ds_bpermute_b32 v18, v8, v80
	global_load_dwordx4 v[8:11], v[180:181], off offset:3136
	global_load_dwordx4 v[12:15], v[180:181], off offset:3168
	v_lshlrev_b64 v[16:17], 11, v[182:183]
	v_lshl_add_u64 v[16:17], s[68:69], 0, v[16:17]
	v_lshlrev_b32_e32 v32, 1, v185
	s_waitcnt lgkmcnt(0)
	v_div_scale_f32 v19, s[0:1], v18, v18, 1.0
	v_rcp_f32_e32 v20, v19
	v_div_scale_f32 v21, vcc, 1.0, v18, 1.0
	v_lshl_add_u64 v[16:17], v[16:17], 0, s[62:63]
	v_fma_f32 v22, -v19, v20, 1.0
	v_fmac_f32_e32 v20, v22, v20
	v_mul_f32_e32 v22, v21, v20
	v_fma_f32 v23, -v19, v22, v21
	v_fmac_f32_e32 v22, v23, v20
	v_fma_f32 v19, -v19, v22, v21
	v_div_fmas_f32 v19, v19, v20, v22
	v_div_fixup_f32 v18, v19, v18, 1.0
	v_lshl_add_u64 v[16:17], v[16:17], 0, v[32:33]
	v_pk_mul_f32 v[20:21], v[64:65], v[18:19] op_sel_hi:[1,0]
	v_pk_mul_f32 v[22:23], v[66:67], v[18:19] op_sel_hi:[1,0]
	v_pk_mul_f32 v[24:25], v[68:69], v[18:19] op_sel_hi:[1,0]
	v_pk_mul_f32 v[26:27], v[70:71], v[18:19] op_sel_hi:[1,0]
	v_pk_mul_f32 v[28:29], v[72:73], v[18:19] op_sel_hi:[1,0]
	v_pk_mul_f32 v[30:31], v[74:75], v[18:19] op_sel_hi:[1,0]
	v_pk_mul_f32 v[34:35], v[76:77], v[18:19] op_sel_hi:[1,0]
	v_pk_mul_f32 v[36:37], v[78:79], v[18:19] op_sel_hi:[1,0]
	s_waitcnt vmcnt(3)
	v_mov_b32_e32 v19, v2
	v_mov_b32_e32 v32, v3
	s_waitcnt vmcnt(2)
	v_mov_b32_e32 v43, v6
	v_mov_b32_e32 v45, v7
	v_permlane32_swap_b32_e32 v0, v19
	v_permlane32_swap_b32_e32 v1, v32
	v_permlane32_swap_b32_e32 v4, v43
	v_permlane32_swap_b32_e32 v5, v45
	v_lshlrev_b32_e32 v2, 16, v0
	v_and_b32_e32 v3, 0xffff0000, v0
	v_lshlrev_b32_e32 v0, 16, v1
	v_and_b32_e32 v1, 0xffff0000, v1
	v_lshlrev_b32_e32 v6, 16, v19
	v_and_b32_e32 v7, 0xffff0000, v19
	v_lshlrev_b32_e32 v38, 16, v32
	v_and_b32_e32 v39, 0xffff0000, v32
	v_lshlrev_b32_e32 v40, 16, v4
	v_and_b32_e32 v41, 0xffff0000, v4
	v_lshlrev_b32_e32 v42, 16, v43
	v_and_b32_e32 v43, 0xffff0000, v43
	v_lshlrev_b32_e32 v4, 16, v5
	v_and_b32_e32 v5, 0xffff0000, v5
	v_lshlrev_b32_e32 v44, 16, v45
	v_and_b32_e32 v45, 0xffff0000, v45
	v_pk_mul_f32 v[2:3], v[20:21], v[2:3]
	v_pk_mul_f32 v[20:21], v[22:23], v[0:1]
	v_pk_mul_f32 v[6:7], v[24:25], v[6:7]
	v_pk_mul_f32 v[22:23], v[26:27], v[38:39]
	v_pk_mul_f32 v[24:25], v[28:29], v[40:41]
	v_pk_mul_f32 v[28:29], v[34:35], v[42:43]
	v_pk_mul_f32 v[26:27], v[30:31], v[4:5]
	v_pk_mul_f32 v[30:31], v[36:37], v[44:45]
	v_cvt_pk_bf16_f32 v0, v2, v3
	v_cvt_pk_bf16_f32 v1, v20, v21
	v_cvt_pk_bf16_f32 v2, v6, v7
	v_cvt_pk_bf16_f32 v3, v22, v23
	v_cvt_pk_bf16_f32 v4, v24, v25
	v_cvt_pk_bf16_f32 v6, v28, v29
	v_cvt_pk_bf16_f32 v5, v26, v27
	v_cvt_pk_bf16_f32 v7, v30, v31
	v_permlane32_swap_b32_e32 v0, v2
	v_permlane32_swap_b32_e32 v1, v3
	v_permlane32_swap_b32_e32 v4, v6
	v_permlane32_swap_b32_e32 v5, v7
	global_store_dwordx4 v[16:17], v[0:3], off
	global_store_dwordx4 v[16:17], v[4:7], off offset:32
	s_nop 0
	v_pk_mul_f32 v[2:3], v[48:49], v[18:19] op_sel_hi:[1,0]
	s_waitcnt vmcnt(3)
	v_mov_b32_e32 v6, v10
	s_nop 1
	v_permlane32_swap_b32_e32 v8, v6
	v_mov_b32_e32 v7, v11
	s_nop 1
	v_permlane32_swap_b32_e32 v9, v7
	v_lshlrev_b32_e32 v0, 16, v8
	v_and_b32_e32 v1, 0xffff0000, v8
	v_pk_mul_f32 v[0:1], v[2:3], v[0:1]
	v_lshlrev_b32_e32 v2, 16, v9
	v_and_b32_e32 v3, 0xffff0000, v9
	v_pk_mul_f32 v[4:5], v[50:51], v[18:19] op_sel_hi:[1,0]
	v_cvt_pk_bf16_f32 v0, v0, v1
	v_pk_mul_f32 v[2:3], v[4:5], v[2:3]
	v_pk_mul_f32 v[4:5], v[52:53], v[18:19] op_sel_hi:[1,0]
	v_cvt_pk_bf16_f32 v1, v2, v3
	v_lshlrev_b32_e32 v2, 16, v6
	v_and_b32_e32 v3, 0xffff0000, v6
	s_waitcnt vmcnt(2)
	v_mov_b32_e32 v10, v14
	v_pk_mul_f32 v[2:3], v[4:5], v[2:3]
	v_lshlrev_b32_e32 v4, 16, v7
	v_and_b32_e32 v5, 0xffff0000, v7
	v_pk_mul_f32 v[6:7], v[54:55], v[18:19] op_sel_hi:[1,0]
	v_permlane32_swap_b32_e32 v12, v10
	v_mov_b32_e32 v11, v15
	v_pk_mul_f32 v[4:5], v[6:7], v[4:5]
	s_nop 0
	v_permlane32_swap_b32_e32 v13, v11
	v_cvt_pk_bf16_f32 v2, v2, v3
	v_cvt_pk_bf16_f32 v3, v4, v5
	v_lshlrev_b32_e32 v4, 16, v12
	v_and_b32_e32 v5, 0xffff0000, v12
	v_pk_mul_f32 v[6:7], v[56:57], v[18:19] op_sel_hi:[1,0]
	v_pk_mul_f32 v[8:9], v[58:59], v[18:19] op_sel_hi:[1,0]
	v_pk_mul_f32 v[4:5], v[6:7], v[4:5]
	v_lshlrev_b32_e32 v6, 16, v13
	v_and_b32_e32 v7, 0xffff0000, v13
	v_pk_mul_f32 v[6:7], v[8:9], v[6:7]
	v_cvt_pk_bf16_f32 v4, v4, v5
	v_cvt_pk_bf16_f32 v5, v6, v7
	v_lshlrev_b32_e32 v6, 16, v10
	v_and_b32_e32 v7, 0xffff0000, v10
	v_pk_mul_f32 v[8:9], v[60:61], v[18:19] op_sel_hi:[1,0]
	v_permlane32_swap_b32_e32 v0, v2
	v_pk_mul_f32 v[6:7], v[8:9], v[6:7]
	v_lshlrev_b32_e32 v8, 16, v11
	v_and_b32_e32 v9, 0xffff0000, v11
	v_pk_mul_f32 v[10:11], v[62:63], v[18:19] op_sel_hi:[1,0]
	v_cvt_pk_bf16_f32 v6, v6, v7
	v_pk_mul_f32 v[8:9], v[10:11], v[8:9]
	v_permlane32_swap_b32_e32 v1, v3
	v_cvt_pk_bf16_f32 v7, v8, v9
	v_permlane32_swap_b32_e32 v4, v6
	s_nop 0
	v_permlane32_swap_b32_e32 v5, v7
	global_store_dwordx4 v[16:17], v[0:3], off offset:64
	global_store_dwordx4 v[16:17], v[4:7], off offset:96
.LBB0_568:
	v_readlane_b32 s98, v255, 14
	s_nop 3
	s_cmp_lg_u32 s98, 0
	s_cbranch_scc1 .Lmoba_dq_latch2
	s_mov_b32 s98, 1
	s_nop 0
	v_writelane_b32 v255, s98, 14
	s_cmpk_gt_i32 s76, 0x80
	s_cbranch_scc1 .Lmoba_dq_latch2
	s_mov_b64 s[98:99], exec
	v_readlane_b32 s100, v255, 1
	v_readlane_b32 s101, v255, 2
	s_nop 1
	s_mov_b64 exec, s[100:101]
	s_cbranch_execz .Lb3w_skip_a
	v_readlane_b32 s100, v255, 11
	s_nop 3
	v_sub_u32_e64 v230, 4, s100
	v_readlane_b32 s100, v255, 5
	v_readlane_b32 s101, v255, 6
	v_mov_b32_e32 v217, 0x3500
	v_mov_b32_e32 v231, 0
	s_nop 4
.Lb3w_loop_a:
	global_load_dword v254, v217, s[100:101] sc1
	s_waitcnt vmcnt(0)
	v_cmp_ge_u32_e32 vcc, v254, v230
	s_cbranch_vccnz .Lb3w_done_a
	s_sleep 1
	v_add_u32_e32 v231, 1, v231
	v_cmp_gt_u32_e32 vcc, 0x4000, v231
	s_cbranch_vccnz .Lb3w_loop_a
.Lb3w_done_a:
	buffer_inv sc1
	s_waitcnt vmcnt(0)
.Lb3w_skip_a:
	s_mov_b64 exec, s[98:99]
	s_barrier
	s_branch .Lscan_entry
.Lmoba_dq_latch2:
	s_waitcnt lgkmcnt(0)
	s_barrier
	v_mov_b32_e32 v217, 0x10008
	ds_read_b32 v217, v217
	s_waitcnt lgkmcnt(0)
	s_nop 0
	v_readfirstlane_b32 s14, v217
	s_nop 3
	s_add_i32 s14, s14, 64
	s_cmpk_gt_u32 s14, 0x7f
	s_cbranch_scc1 .LBB0_643
	s_branch .LBB0_574

.LBB0_610:
	s_or_b64 exec, exec, s[4:5]
	v_readlane_b32 s100, v255, 1
	v_readlane_b32 s101, v255, 2
	s_mov_b64 s[98:99], exec
	s_nop 1
	s_mov_b64 exec, s[100:101]
	s_cbranch_execz .Lmoba_dq_skip
	s_lshl_b32 s100, s73, 4
	v_mov_b32_e32 v217, s100
	v_mov_b32_e32 v254, 1
	s_add_u32 s100, s58, 0xfd29000
	s_addc_u32 s101, s59, 0
	global_atomic_add v254, v217, v254, s[100:101] sc0
.Lmoba_dq_skip:
	s_mov_b64 exec, s[98:99]
	s_add_i32 s12, s85, -1
	s_add_u32 s0, s66, s62
	v_cmp_eq_u32_e32 vcc, 0, v201
	s_addc_u32 s1, s67, 0
	v_lshlrev_b32_e32 v32, 1, v32
	v_mov_b32_e32 v46, v33
	v_mov_b32_e32 v47, v33
	v_cndmask_b32_e32 v176, 0, v200, vcc
	v_lshlrev_b32_e32 v215, 2, v34
	v_lshl_add_u64 v[194:195], s[0:1], 0, v[32:33]
	v_mov_b32_e32 v32, v33
	v_mov_b32_e32 v34, v33
	v_mov_b32_e32 v35, v33
	v_mov_b32_e32 v36, v33
	v_mov_b32_e32 v37, v33
	v_mov_b32_e32 v38, v33
	v_mov_b32_e32 v39, v33
	v_mov_b32_e32 v40, v33
	v_mov_b32_e32 v41, v33
	v_mov_b32_e32 v42, v33
	v_mov_b32_e32 v43, v33
	v_mov_b32_e32 v44, v33
	v_mov_b32_e32 v45, v33
	v_mov_b64_e32 v[62:63], v[46:47]
	v_mov_b64_e32 v[78:79], v[46:47]
	v_mov_b64_e32 v[94:95], v[46:47]
	v_mov_b64_e32 v[110:111], v[46:47]
	v_mov_b64_e32 v[126:127], v[46:47]
	v_or_b32_e32 v214, 31, v202
	s_mov_b32 s15, 0
	v_mov_b32_e32 v177, v176
	v_mov_b32_e32 v178, v176
	v_mov_b32_e32 v179, v176
	v_mov_b32_e32 v216, 0xf149f2ca
	s_mov_b32 s14, 5
	s_movk_i32 s13, 0x80
	v_mov_b64_e32 v[60:61], v[44:45]
	v_mov_b64_e32 v[58:59], v[42:43]
	v_mov_b64_e32 v[56:57], v[40:41]
	v_mov_b64_e32 v[54:55], v[38:39]
	v_mov_b64_e32 v[52:53], v[36:37]
	v_mov_b64_e32 v[50:51], v[34:35]
	v_mov_b64_e32 v[48:49], v[32:33]
	v_mov_b64_e32 v[76:77], v[44:45]
	v_mov_b64_e32 v[74:75], v[42:43]
	v_mov_b64_e32 v[72:73], v[40:41]
	v_mov_b64_e32 v[70:71], v[38:39]
	v_mov_b64_e32 v[68:69], v[36:37]
	v_mov_b64_e32 v[66:67], v[34:35]
	v_mov_b64_e32 v[64:65], v[32:33]
	v_mov_b64_e32 v[92:93], v[44:45]
	v_mov_b64_e32 v[90:91], v[42:43]
	v_mov_b64_e32 v[88:89], v[40:41]
	v_mov_b64_e32 v[86:87], v[38:39]
	v_mov_b64_e32 v[84:85], v[36:37]
	v_mov_b64_e32 v[82:83], v[34:35]
	v_mov_b64_e32 v[80:81], v[32:33]
	v_mov_b64_e32 v[108:109], v[44:45]
	v_mov_b64_e32 v[106:107], v[42:43]
	v_mov_b64_e32 v[104:105], v[40:41]
	v_mov_b64_e32 v[102:103], v[38:39]
	v_mov_b64_e32 v[100:101], v[36:37]
	v_mov_b64_e32 v[98:99], v[34:35]
	v_mov_b64_e32 v[96:97], v[32:33]
	v_mov_b64_e32 v[124:125], v[44:45]
	v_mov_b64_e32 v[122:123], v[42:43]
	v_mov_b64_e32 v[120:121], v[40:41]
	v_mov_b64_e32 v[118:119], v[38:39]
	v_mov_b64_e32 v[116:117], v[36:37]
	v_mov_b64_e32 v[114:115], v[34:35]
	v_mov_b64_e32 v[112:113], v[32:33]

.Lmoba_fuse_a:
	s_lshl_b32 s0, s17, 13
	s_lshl_b32 s1, s15, 13
	v_add_u32_e32 v230, s0, v204
	v_add_u32_e32 v231, s0, v205
	v_add_u32_e32 v232, s0, v206
	v_add_u32_e32 v233, s0, v208
	ds_read_b128 v[218:221], v230 offset:4096
	ds_read_b128 v[222:225], v230 offset:8192
	ds_read_b128 v[226:229], v231 offset:4096
	ds_read_b128 v[234:237], v231 offset:8192
	ds_read_b128 v[238:241], v232 offset:4096
	ds_read_b128 v[242:245], v232 offset:8192
	ds_read_b128 v[246:249], v233 offset:4096
	ds_read_b128 v[250:253], v233 offset:8192
	v_add_u32_e32 v230, s1, v204
	v_add_u32_e32 v231, s1, v205
	v_add_u32_e32 v232, s1, v206
	v_add_u32_e32 v233, s1, v208
	ds_read_b128 v[34:37], v230 offset:28672
	ds_read_b128 v[42:45], v230 offset:32768
	v_max_f32_e32 v32, v1, v1
	v_max_f32_e32 v39, v0, v0
	v_max_f32_e32 v32, v39, v32
	v_max3_f32 v32, v32, v2, v3
	v_max3_f32 v32, v32, v4, v5
	v_max3_f32 v32, v32, v6, v7
	v_max3_f32 v32, v32, v8, v9
	v_max3_f32 v32, v32, v10, v11
	v_max3_f32 v32, v32, v12, v13
	v_max3_f32 v32, v32, v14, v15
	s_waitcnt lgkmcnt(9)
	v_mfma_f32_32x32x16_bf16 v[96:111], v[218:221], v[128:131], 0
	v_max3_f32 v32, v32, v16, v17
	v_max3_f32 v32, v32, v18, v19
	v_max3_f32 v32, v32, v20, v21
	v_max3_f32 v32, v32, v22, v23
	v_max3_f32 v32, v32, v24, v25
	v_max3_f32 v32, v32, v26, v27
	s_waitcnt lgkmcnt(8)
	v_mfma_f32_32x32x16_bf16 v[112:127], v[222:225], v[128:131], 0
	ds_read_b128 v[218:221], v231 offset:28672
	ds_read_b128 v[222:225], v231 offset:32768
	v_max3_f32 v32, v32, v28, v29
	v_max3_f32 v32, v32, v30, v31
	v_mov_b32_e32 v39, v32
	s_lshl_b32 s4, 1, s16
	v_and_b32_e32 v38, s4, v203
	v_permlane32_swap_b32_e32 v39, v32
	v_cmp_ne_u32_e32 vcc, 0, v38
	v_max_f32_e32 v39, v39, v39
	v_max_f32_e32 v32, v32, v39
	s_waitcnt lgkmcnt(9)
	v_mfma_f32_32x32x16_bf16 v[96:111], v[226:229], v[132:135], v[96:111]
	v_cndmask_b32_e32 v32, v199, v32, vcc
	v_max_f32_e32 v39, v216, v216
	v_max_f32_e32 v32, v39, v32
	v_sub_f32_e32 v39, v216, v32
	v_cmp_lt_f32_e64 s[4:5], s82, v32
	v_mul_f32_e32 v39, 0x3e38aa3b, v39
	v_mul_f32_e32 v38, 0xbe38aa3b, v32
	s_and_b64 vcc, vcc, s[4:5]
	s_waitcnt lgkmcnt(8)
	v_mfma_f32_32x32x16_bf16 v[112:127], v[234:237], v[132:135], v[112:127]
	ds_read_b128 v[226:229], v232 offset:28672
	ds_read_b128 v[234:237], v232 offset:32768
	v_exp_f32_e32 v46, v39
	v_cndmask_b32_e32 v47, v199, v38, vcc
	v_mov_b32_e32 v216, v32
	v_fmamk_f32 v0, v0, 0x3e38aa3b, v47
	v_fmamk_f32 v1, v1, 0x3e38aa3b, v47
	v_fmamk_f32 v2, v2, 0x3e38aa3b, v47
	v_fmamk_f32 v3, v3, 0x3e38aa3b, v47
	v_fmamk_f32 v4, v4, 0x3e38aa3b, v47
	v_fmamk_f32 v5, v5, 0x3e38aa3b, v47
	v_fmamk_f32 v6, v6, 0x3e38aa3b, v47
	v_fmamk_f32 v7, v7, 0x3e38aa3b, v47
	s_waitcnt lgkmcnt(9)
	v_mfma_f32_32x32x16_bf16 v[96:111], v[238:241], v[136:139], v[96:111]
	v_exp_f32_e32 v0, v0
	v_exp_f32_e32 v1, v1
	v_exp_f32_e32 v2, v2
	v_exp_f32_e32 v3, v3
	s_waitcnt lgkmcnt(8)
	v_mfma_f32_32x32x16_bf16 v[112:127], v[242:245], v[136:139], v[112:127]
	ds_read_b128 v[238:241], v233 offset:28672
	ds_read_b128 v[242:245], v233 offset:32768
	v_exp_f32_e32 v4, v4
	v_exp_f32_e32 v5, v5
	v_exp_f32_e32 v6, v6
	v_exp_f32_e32 v7, v7
	s_waitcnt lgkmcnt(9)
	v_mfma_f32_32x32x16_bf16 v[96:111], v[246:249], v[140:143], v[96:111]
	v_pk_mul_f32 v[64:65], v[64:65], v[46:47] op_sel_hi:[1,0]
	v_pk_mul_f32 v[66:67], v[66:67], v[46:47] op_sel_hi:[1,0]
	v_pk_mul_f32 v[68:69], v[68:69], v[46:47] op_sel_hi:[1,0]
	v_pk_mul_f32 v[70:71], v[70:71], v[46:47] op_sel_hi:[1,0]
	v_pk_mul_f32 v[72:73], v[72:73], v[46:47] op_sel_hi:[1,0]
	v_pk_mul_f32 v[74:75], v[74:75], v[46:47] op_sel_hi:[1,0]
	v_pk_mul_f32 v[76:77], v[76:77], v[46:47] op_sel_hi:[1,0]
	v_pk_mul_f32 v[78:79], v[78:79], v[46:47] op_sel_hi:[1,0]
	s_waitcnt lgkmcnt(8)
	v_mfma_f32_32x32x16_bf16 v[112:127], v[250:253], v[140:143], v[112:127]
	v_pk_mul_f32 v[48:49], v[48:49], v[46:47] op_sel_hi:[1,0]
	v_pk_mul_f32 v[50:51], v[50:51], v[46:47] op_sel_hi:[1,0]
	v_pk_mul_f32 v[52:53], v[52:53], v[46:47] op_sel_hi:[1,0]
	v_pk_mul_f32 v[54:55], v[54:55], v[46:47] op_sel_hi:[1,0]
	v_pk_mul_f32 v[56:57], v[56:57], v[46:47] op_sel_hi:[1,0]
	v_pk_mul_f32 v[58:59], v[58:59], v[46:47] op_sel_hi:[1,0]
	v_pk_mul_f32 v[60:61], v[60:61], v[46:47] op_sel_hi:[1,0]
	v_pk_mul_f32 v[62:63], v[62:63], v[46:47] op_sel_hi:[1,0]
	v_mul_f32_e32 v80, v80, v46
	v_cvt_pk_bf16_f32 v38, v0, v1
	v_cvt_pk_bf16_f32 v39, v2, v3
	v_cvt_pk_bf16_f32 v40, v4, v5
	v_cvt_pk_bf16_f32 v41, v6, v7
	v_fmamk_f32 v8, v8, 0x3e38aa3b, v47
	v_fmamk_f32 v9, v9, 0x3e38aa3b, v47
	s_waitcnt lgkmcnt(7)
	v_mfma_f32_32x32x16_bf16 v[64:79], v[34:37], v[38:41], v[64:79]
	v_fmamk_f32 v10, v10, 0x3e38aa3b, v47
	v_fmamk_f32 v11, v11, 0x3e38aa3b, v47
	v_fmamk_f32 v12, v12, 0x3e38aa3b, v47
	v_fmamk_f32 v13, v13, 0x3e38aa3b, v47
	v_fmamk_f32 v14, v14, 0x3e38aa3b, v47
	v_fmamk_f32 v15, v15, 0x3e38aa3b, v47
	v_exp_f32_e32 v8, v8
	s_waitcnt lgkmcnt(6)
	v_mfma_f32_32x32x16_bf16 v[48:63], v[42:45], v[38:41], v[48:63]
	v_exp_f32_e32 v9, v9
	v_exp_f32_e32 v10, v10
	v_mfma_f32_32x32x16_bf16 v[80:95], v[176:179], v[38:41], v[80:95]
	v_exp_f32_e32 v11, v11
	v_exp_f32_e32 v12, v12
	v_exp_f32_e32 v13, v13
	v_exp_f32_e32 v14, v14
	v_exp_f32_e32 v15, v15
	v_cvt_pk_bf16_f32 v38, v8, v9
	v_cvt_pk_bf16_f32 v39, v10, v11
	v_cvt_pk_bf16_f32 v40, v12, v13
	v_cvt_pk_bf16_f32 v41, v14, v15
	v_fmamk_f32 v16, v16, 0x3e38aa3b, v47
	v_fmamk_f32 v17, v17, 0x3e38aa3b, v47
	s_waitcnt lgkmcnt(5)
	v_mfma_f32_32x32x16_bf16 v[64:79], v[218:221], v[38:41], v[64:79]
	v_fmamk_f32 v18, v18, 0x3e38aa3b, v47
	v_fmamk_f32 v19, v19, 0x3e38aa3b, v47
	v_fmamk_f32 v20, v20, 0x3e38aa3b, v47
	v_fmamk_f32 v21, v21, 0x3e38aa3b, v47
	v_fmamk_f32 v22, v22, 0x3e38aa3b, v47
	v_fmamk_f32 v23, v23, 0x3e38aa3b, v47
	v_exp_f32_e32 v16, v16
	s_waitcnt lgkmcnt(4)
	v_mfma_f32_32x32x16_bf16 v[48:63], v[222:225], v[38:41], v[48:63]
	v_exp_f32_e32 v17, v17
	v_exp_f32_e32 v18, v18
	v_mfma_f32_32x32x16_bf16 v[80:95], v[176:179], v[38:41], v[80:95]
	v_exp_f32_e32 v19, v19
	v_exp_f32_e32 v20, v20
	v_exp_f32_e32 v21, v21
	v_exp_f32_e32 v22, v22
	v_exp_f32_e32 v23, v23
	v_cvt_pk_bf16_f32 v38, v16, v17
	v_cvt_pk_bf16_f32 v39, v18, v19
	v_cvt_pk_bf16_f32 v40, v20, v21
	v_cvt_pk_bf16_f32 v41, v22, v23
	v_fmamk_f32 v24, v24, 0x3e38aa3b, v47
	v_fmamk_f32 v25, v25, 0x3e38aa3b, v47
	s_waitcnt lgkmcnt(3)
	v_mfma_f32_32x32x16_bf16 v[64:79], v[226:229], v[38:41], v[64:79]
	v_fmamk_f32 v26, v26, 0x3e38aa3b, v47
	v_fmamk_f32 v27, v27, 0x3e38aa3b, v47
	v_fmamk_f32 v28, v28, 0x3e38aa3b, v47
	v_fmamk_f32 v29, v29, 0x3e38aa3b, v47
	v_fmamk_f32 v30, v30, 0x3e38aa3b, v47
	v_fmamk_f32 v31, v31, 0x3e38aa3b, v47
	v_exp_f32_e32 v24, v24
	s_waitcnt lgkmcnt(2)
	v_mfma_f32_32x32x16_bf16 v[48:63], v[234:237], v[38:41], v[48:63]
	v_exp_f32_e32 v25, v25
	v_exp_f32_e32 v26, v26
	v_mfma_f32_32x32x16_bf16 v[80:95], v[176:179], v[38:41], v[80:95]
	v_exp_f32_e32 v27, v27
	v_exp_f32_e32 v28, v28
	v_exp_f32_e32 v29, v29
	v_exp_f32_e32 v30, v30
	v_exp_f32_e32 v31, v31
	v_cvt_pk_bf16_f32 v38, v24, v25
	v_cvt_pk_bf16_f32 v39, v26, v27
	v_cvt_pk_bf16_f32 v40, v28, v29
	v_cvt_pk_bf16_f32 v41, v30, v31
	s_nop 1
	s_waitcnt lgkmcnt(1)
	v_mfma_f32_32x32x16_bf16 v[64:79], v[238:241], v[38:41], v[64:79]
	s_waitcnt lgkmcnt(0)
	v_mfma_f32_32x32x16_bf16 v[48:63], v[242:245], v[38:41], v[48:63]
	v_mfma_f32_32x32x16_bf16 v[80:95], v[176:179], v[38:41], v[80:95]
	s_branch .LBB0_624
.Lmoba_fuse_b:
	s_mov_b32 s0, s7
	s_lshl_b32 s1, s17, 13
	v_add_u32_e32 v230, s0, v204
	v_add_u32_e32 v231, s0, v205
	v_add_u32_e32 v232, s0, v206
	v_add_u32_e32 v233, s0, v208
	ds_read_b128 v[218:221], v230 offset:4096
	ds_read_b128 v[222:225], v230 offset:8192
	ds_read_b128 v[226:229], v231 offset:4096
	ds_read_b128 v[234:237], v231 offset:8192
	ds_read_b128 v[238:241], v232 offset:4096
	ds_read_b128 v[242:245], v232 offset:8192
	ds_read_b128 v[246:249], v233 offset:4096
	ds_read_b128 v[250:253], v233 offset:8192
	v_add_u32_e32 v230, s1, v204
	v_add_u32_e32 v231, s1, v205
	v_add_u32_e32 v232, s1, v206
	v_add_u32_e32 v233, s1, v208
	ds_read_b128 v[34:37], v230 offset:28672
	ds_read_b128 v[42:45], v230 offset:32768
	v_max_f32_e32 v32, v97, v97
	v_max_f32_e32 v39, v96, v96
	v_max_f32_e32 v32, v39, v32
	v_max3_f32 v32, v32, v98, v99
	v_max3_f32 v32, v32, v100, v101
	v_max3_f32 v32, v32, v102, v103
	v_max3_f32 v32, v32, v104, v105
	v_max3_f32 v32, v32, v106, v107
	v_max3_f32 v32, v32, v108, v109
	v_max3_f32 v32, v32, v110, v111
	s_waitcnt lgkmcnt(9)
	v_mfma_f32_32x32x16_bf16 v[0:15], v[218:221], v[128:131], 0
	v_max3_f32 v32, v32, v112, v113
	v_max3_f32 v32, v32, v114, v115
	v_max3_f32 v32, v32, v116, v117
	v_max3_f32 v32, v32, v118, v119
	v_max3_f32 v32, v32, v120, v121
	v_max3_f32 v32, v32, v122, v123
	s_waitcnt lgkmcnt(8)
	v_mfma_f32_32x32x16_bf16 v[16:31], v[222:225], v[128:131], 0
	ds_read_b128 v[218:221], v231 offset:28672
	ds_read_b128 v[222:225], v231 offset:32768
	v_max3_f32 v32, v32, v124, v125
	v_max3_f32 v32, v32, v126, v127
	v_mov_b32_e32 v39, v32
	s_lshl_b32 s4, 1, s16
	v_and_b32_e32 v38, s4, v203
	v_permlane32_swap_b32_e32 v39, v32
	v_cmp_ne_u32_e32 vcc, 0, v38
	v_max_f32_e32 v39, v39, v39
	v_max_f32_e32 v32, v32, v39
	s_waitcnt lgkmcnt(9)
	v_mfma_f32_32x32x16_bf16 v[0:15], v[226:229], v[132:135], v[0:15]
	v_cndmask_b32_e32 v32, v199, v32, vcc
	v_max_f32_e32 v39, v216, v216
	v_max_f32_e32 v32, v39, v32
	v_sub_f32_e32 v39, v216, v32
	v_cmp_lt_f32_e64 s[4:5], s82, v32
	v_mul_f32_e32 v39, 0x3e38aa3b, v39
	v_mul_f32_e32 v38, 0xbe38aa3b, v32
	s_and_b64 vcc, vcc, s[4:5]
	s_waitcnt lgkmcnt(8)
	v_mfma_f32_32x32x16_bf16 v[16:31], v[234:237], v[132:135], v[16:31]
	ds_read_b128 v[226:229], v232 offset:28672
	ds_read_b128 v[234:237], v232 offset:32768
	v_exp_f32_e32 v46, v39
	v_cndmask_b32_e32 v47, v199, v38, vcc
	v_mov_b32_e32 v216, v32
	v_fmamk_f32 v96, v96, 0x3e38aa3b, v47
	v_fmamk_f32 v97, v97, 0x3e38aa3b, v47
	v_fmamk_f32 v98, v98, 0x3e38aa3b, v47
	v_fmamk_f32 v99, v99, 0x3e38aa3b, v47
	v_fmamk_f32 v100, v100, 0x3e38aa3b, v47
	v_fmamk_f32 v101, v101, 0x3e38aa3b, v47
	v_fmamk_f32 v102, v102, 0x3e38aa3b, v47
	v_fmamk_f32 v103, v103, 0x3e38aa3b, v47
	s_waitcnt lgkmcnt(9)
	v_mfma_f32_32x32x16_bf16 v[0:15], v[238:241], v[136:139], v[0:15]
	v_exp_f32_e32 v96, v96
	v_exp_f32_e32 v97, v97
	v_exp_f32_e32 v98, v98
	v_exp_f32_e32 v99, v99
	s_waitcnt lgkmcnt(8)
	v_mfma_f32_32x32x16_bf16 v[16:31], v[242:245], v[136:139], v[16:31]
	ds_read_b128 v[238:241], v233 offset:28672
	ds_read_b128 v[242:245], v233 offset:32768
	v_exp_f32_e32 v100, v100
	v_exp_f32_e32 v101, v101
	v_exp_f32_e32 v102, v102
	v_exp_f32_e32 v103, v103
	s_waitcnt lgkmcnt(9)
	v_mfma_f32_32x32x16_bf16 v[0:15], v[246:249], v[140:143], v[0:15]
	v_pk_mul_f32 v[64:65], v[64:65], v[46:47] op_sel_hi:[1,0]
	v_pk_mul_f32 v[66:67], v[66:67], v[46:47] op_sel_hi:[1,0]
	v_pk_mul_f32 v[68:69], v[68:69], v[46:47] op_sel_hi:[1,0]
	v_pk_mul_f32 v[70:71], v[70:71], v[46:47] op_sel_hi:[1,0]
	v_pk_mul_f32 v[72:73], v[72:73], v[46:47] op_sel_hi:[1,0]
	v_pk_mul_f32 v[74:75], v[74:75], v[46:47] op_sel_hi:[1,0]
	v_pk_mul_f32 v[76:77], v[76:77], v[46:47] op_sel_hi:[1,0]
	v_pk_mul_f32 v[78:79], v[78:79], v[46:47] op_sel_hi:[1,0]
	s_waitcnt lgkmcnt(8)
	v_mfma_f32_32x32x16_bf16 v[16:31], v[250:253], v[140:143], v[16:31]
	v_pk_mul_f32 v[48:49], v[48:49], v[46:47] op_sel_hi:[1,0]
	v_pk_mul_f32 v[50:51], v[50:51], v[46:47] op_sel_hi:[1,0]
	v_pk_mul_f32 v[52:53], v[52:53], v[46:47] op_sel_hi:[1,0]
	v_pk_mul_f32 v[54:55], v[54:55], v[46:47] op_sel_hi:[1,0]
	v_pk_mul_f32 v[56:57], v[56:57], v[46:47] op_sel_hi:[1,0]
	v_pk_mul_f32 v[58:59], v[58:59], v[46:47] op_sel_hi:[1,0]
	v_pk_mul_f32 v[60:61], v[60:61], v[46:47] op_sel_hi:[1,0]
	v_pk_mul_f32 v[62:63], v[62:63], v[46:47] op_sel_hi:[1,0]
	v_mul_f32_e32 v80, v80, v46
	v_cvt_pk_bf16_f32 v38, v96, v97
	v_cvt_pk_bf16_f32 v39, v98, v99
	v_cvt_pk_bf16_f32 v40, v100, v101
	v_cvt_pk_bf16_f32 v41, v102, v103
	v_fmamk_f32 v104, v104, 0x3e38aa3b, v47
	v_fmamk_f32 v105, v105, 0x3e38aa3b, v47
	s_waitcnt lgkmcnt(7)
	v_mfma_f32_32x32x16_bf16 v[64:79], v[34:37], v[38:41], v[64:79]
	v_fmamk_f32 v106, v106, 0x3e38aa3b, v47
	v_fmamk_f32 v107, v107, 0x3e38aa3b, v47
	v_fmamk_f32 v108, v108, 0x3e38aa3b, v47
	v_fmamk_f32 v109, v109, 0x3e38aa3b, v47
	v_fmamk_f32 v110, v110, 0x3e38aa3b, v47
	v_fmamk_f32 v111, v111, 0x3e38aa3b, v47
	v_exp_f32_e32 v104, v104
	s_waitcnt lgkmcnt(6)
	v_mfma_f32_32x32x16_bf16 v[48:63], v[42:45], v[38:41], v[48:63]
	v_exp_f32_e32 v105, v105
	v_exp_f32_e32 v106, v106
	v_mfma_f32_32x32x16_bf16 v[80:95], v[176:179], v[38:41], v[80:95]
	v_exp_f32_e32 v107, v107
	v_exp_f32_e32 v108, v108
	v_exp_f32_e32 v109, v109
	v_exp_f32_e32 v110, v110
	v_exp_f32_e32 v111, v111
	v_cvt_pk_bf16_f32 v38, v104, v105
	v_cvt_pk_bf16_f32 v39, v106, v107
	v_cvt_pk_bf16_f32 v40, v108, v109
	v_cvt_pk_bf16_f32 v41, v110, v111
	v_fmamk_f32 v112, v112, 0x3e38aa3b, v47
	v_fmamk_f32 v113, v113, 0x3e38aa3b, v47
	s_waitcnt lgkmcnt(5)
	v_mfma_f32_32x32x16_bf16 v[64:79], v[218:221], v[38:41], v[64:79]
	v_fmamk_f32 v114, v114, 0x3e38aa3b, v47
	v_fmamk_f32 v115, v115, 0x3e38aa3b, v47
	v_fmamk_f32 v116, v116, 0x3e38aa3b, v47
	v_fmamk_f32 v117, v117, 0x3e38aa3b, v47
	v_fmamk_f32 v118, v118, 0x3e38aa3b, v47
	v_fmamk_f32 v119, v119, 0x3e38aa3b, v47
	v_exp_f32_e32 v112, v112
	s_waitcnt lgkmcnt(4)
	v_mfma_f32_32x32x16_bf16 v[48:63], v[222:225], v[38:41], v[48:63]
	v_exp_f32_e32 v113, v113
	v_exp_f32_e32 v114, v114
	v_mfma_f32_32x32x16_bf16 v[80:95], v[176:179], v[38:41], v[80:95]
	v_exp_f32_e32 v115, v115
	v_exp_f32_e32 v116, v116
	v_exp_f32_e32 v117, v117
	v_exp_f32_e32 v118, v118
	v_exp_f32_e32 v119, v119
	v_cvt_pk_bf16_f32 v38, v112, v113
	v_cvt_pk_bf16_f32 v39, v114, v115
	v_cvt_pk_bf16_f32 v40, v116, v117
	v_cvt_pk_bf16_f32 v41, v118, v119
	v_fmamk_f32 v120, v120, 0x3e38aa3b, v47
	v_fmamk_f32 v121, v121, 0x3e38aa3b, v47
	s_waitcnt lgkmcnt(3)
	v_mfma_f32_32x32x16_bf16 v[64:79], v[226:229], v[38:41], v[64:79]
	v_fmamk_f32 v122, v122, 0x3e38aa3b, v47
	v_fmamk_f32 v123, v123, 0x3e38aa3b, v47
	v_fmamk_f32 v124, v124, 0x3e38aa3b, v47
	v_fmamk_f32 v125, v125, 0x3e38aa3b, v47
	v_fmamk_f32 v126, v126, 0x3e38aa3b, v47
	v_fmamk_f32 v127, v127, 0x3e38aa3b, v47
	v_exp_f32_e32 v120, v120
	s_waitcnt lgkmcnt(2)
	v_mfma_f32_32x32x16_bf16 v[48:63], v[234:237], v[38:41], v[48:63]
	v_exp_f32_e32 v121, v121
	v_exp_f32_e32 v122, v122
	v_mfma_f32_32x32x16_bf16 v[80:95], v[176:179], v[38:41], v[80:95]
	v_exp_f32_e32 v123, v123
	v_exp_f32_e32 v124, v124
	v_exp_f32_e32 v125, v125
	v_exp_f32_e32 v126, v126
	v_exp_f32_e32 v127, v127
	v_cvt_pk_bf16_f32 v38, v120, v121
	v_cvt_pk_bf16_f32 v39, v122, v123
	v_cvt_pk_bf16_f32 v40, v124, v125
	v_cvt_pk_bf16_f32 v41, v126, v127
	s_nop 1
	s_waitcnt lgkmcnt(1)
	v_mfma_f32_32x32x16_bf16 v[64:79], v[238:241], v[38:41], v[64:79]
	s_waitcnt lgkmcnt(0)
	v_mfma_f32_32x32x16_bf16 v[48:63], v[242:245], v[38:41], v[48:63]
	v_mfma_f32_32x32x16_bf16 v[80:95], v[176:179], v[38:41], v[80:95]
	s_branch .LBB0_640
.LBB0_643:
	s_mov_b64 s[98:99], exec
	v_readlane_b32 s100, v255, 1
	v_readlane_b32 s101, v255, 2
	s_nop 1
	s_mov_b64 exec, s[100:101]
	s_cbranch_execz .Lb3w_skip_b
	v_readlane_b32 s100, v255, 11
	s_nop 3
	v_sub_u32_e64 v230, 4, s100
	v_readlane_b32 s100, v255, 5
	v_readlane_b32 s101, v255, 6
	v_mov_b32_e32 v217, 0x3500
	v_mov_b32_e32 v231, 0
	s_nop 4

.Lb3w_skip_b:
	s_mov_b64 exec, s[98:99]
	s_barrier
	s_waitcnt vmcnt(0)
	s_barrier
	s_mov_b64 s[4:5], exec
	v_readlane_b32 s0, v255, 1
	v_readlane_b32 s1, v255, 2
	s_and_b64 s[0:1], s[4:5], s[0:1]
	s_mov_b64 exec, s[0:1]
	s_cbranch_execz .LBB0_695
	v_mov_b32_e32 v0, 0x10000
	s_waitcnt vmcnt(0) expcnt(0) lgkmcnt(0)
	ds_read_b32 v2, v0
	v_mov_b32_e32 v0, 0x10004
	ds_read_b32 v0, v0
	s_waitcnt lgkmcnt(1)
	v_cmp_ne_u32_e32 vcc, 0, v2
	s_cbranch_vccnz .LBB0_659
	s_add_u32 s6, s58, 0xfd29200
	s_addc_u32 s7, s59, 0
	s_add_u32 s8, s58, 0xfd29400
	s_addc_u32 s9, s59, 0
	s_add_u32 s10, s58, 0xfd29500
	s_addc_u32 s11, s59, 0
	s_add_u32 s12, s58, 0xfd29600
	s_addc_u32 s13, s59, 0
	s_add_u32 s14, s58, 0xfd29700
	s_addc_u32 s15, s59, 0
	s_add_u32 s16, s58, 0xfd29800
	s_addc_u32 s17, s59, 0
	s_add_u32 s18, s58, 0xfd29900
	s_addc_u32 s19, s59, 0
	s_add_u32 s20, s58, 0xfd29a00
	s_addc_u32 s21, s59, 0
	s_add_u32 s22, s58, 0xfd29b00
	s_addc_u32 s23, s59, 0
	s_add_u32 s24, s58, 0xfd29c00
	s_addc_u32 s25, s59, 0
	s_add_u32 s26, s58, 0xfd29d00
	s_addc_u32 s27, s59, 0
	s_add_u32 s28, s58, 0xfd29e00
	s_addc_u32 s29, s59, 0
	s_add_u32 s30, s58, 0xfd29f00
	s_addc_u32 s31, s59, 0
	s_add_u32 s34, s58, 0xfd2a000
	s_addc_u32 s35, s59, 0
	s_add_u32 s36, s58, 0xfd2a100
	s_addc_u32 s37, s59, 0
	s_add_u32 s40, s58, 0xfd2a200
	v_readlane_b32 s0, v255, 0
	s_addc_u32 s41, s59, 0
	s_mul_i32 s2, s43, s0
	s_add_u32 s52, s58, 0xfd2a300
	s_mul_i32 s2, s2, s42
	s_addc_u32 s53, s59, 0
	s_mov_b32 s33, 1
	v_mov_b32_e32 v16, 0
	s_branch .LBB0_647
